# v42 + DTX: prologue transposes only layer 0 weights; layers 1-3 are converted in the FF1 tail of the previous layer by the 128 workgroups that own one tile fewer
# speedup vs baseline: 1.0100x; 1.0100x over previous
; #define LAS __attribute__((address_space(3)))
; __global__ void __launch_bounds__(NTHR, 2) trunk_fwd(Args a) {
;     extern __shared__ __attribute__((aligned(16))) unsigned char lds_raw[];
;     cg::grid_group grid = cg::this_grid();
;     lds_t* lds = (lds_t*)lds_raw;
;     const int tid = threadIdx.x;
;     const int G = gridDim.x, bx = blockIdx.x;
;     const int vcu = (G % 8 == 0) ? (bx % 8) * (G / 8) + bx / 8 : bx;
;     const int ngw = G * NWAVES;
;     unsigned char* ws = a.ws;
;     volatile LAS unsigned* bst = (volatile LAS unsigned*)(lds + LDS_BYTES - 64);
;     if (threadIdx.x == 0) { bst[0] = 0u; bst[1] = 0u; }
;     __syncthreads();
;     (void)xcd_barrier_post((unsigned*)(ws + WS_CTL), bst);
_Z9trunk_fwd4Args:
	s_load_dwordx2 s[60:61], s[0:1], 0xd0
	v_writelane_b32 v253, s0, 57
	v_writelane_b32 v253, s1, 58
	s_mov_b32 s79, s2
	s_add_u32 s2, s0, 0xd0
	s_addc_u32 s3, s1, 0
	s_mov_b32 s52, s79
	s_waitcnt lgkmcnt(0)
	s_and_b32 s4, s60, 7
	s_cmp_lg_u32 s4, 0
	s_cbranch_scc1 .LBB0_2
	s_ashr_i32 s5, s79, 31
	s_lshr_b32 s5, s5, 29
	s_add_i32 s5, s79, s5
	s_and_b32 s6, s5, -8
	s_ashr_i32 s4, s60, 3
	s_sub_i32 s6, s79, s6
	s_mul_i32 s4, s4, s6
	s_ashr_i32 s5, s5, 3
	s_add_i32 s52, s4, s5

; #define LAS __attribute__((address_space(3)))
; __global__ void __launch_bounds__(NTHR, 2) trunk_fwd(Args a) {
;     ...
;         LAS float* scr = (LAS float*)(lds + wave * 16384);
;         constexpr int I_IN = 16 * 72, I_OUT = 16 * 32, I_1 = 16 * 128, I_2 = 64 * 32, I_L = I_IN + I_OUT + I_1 + I_2;
;         for (int it = gw; it < DEPTH * I_L; it += ngw) { const int l = it / I_L; int r = it % I_L;
;             if (r < I_IN) { transpose_item<true>(a.w_in + (size_t)l * DM * DIN, DM, DIN, WT_IN + (size_t)l * DIN * DM, scr, r, lane); continue; } r -= I_IN;
;             if (r < I_OUT) { transpose_item<true>(a.w_out + (size_t)l * DM * DM, DM, DM, WT_OUT + (size_t)l * DM * DM, scr, r, lane); continue; } r -= I_OUT;
;             if (r < I_1) { transpose_item<true>(a.w_ff1 + (size_t)l * DM * DFF, DM, DFF, WT_1 + (size_t)l * DFF * DM, scr, r, lane); continue; } r -= I_1;
;             transpose_item<true>(a.w_ff2 + (size_t)l * DFF * DM, DFF, DM, WT_2 + (size_t)l * DM * DFF, scr, r, lane); }
.LBB0_27:
	s_load_dwordx16 s[16:31], s[0:1], 0x80
	s_add_u32 s4, s94, 0x1200000
	s_mov_b64 s[82:83], s[50:51]
	s_mov_b64 s[80:81], s[48:49]
	s_mov_b64 s[68:69], s[36:37]
	s_waitcnt lgkmcnt(0)
	v_writelane_b32 v253, s16, 2
	s_mov_b64 s[72:73], s[40:41]
	s_nop 0
	v_writelane_b32 v253, s17, 3
	v_writelane_b32 v253, s18, 4
	v_writelane_b32 v253, s19, 5
	v_writelane_b32 v253, s20, 6
	v_writelane_b32 v253, s21, 7
	v_writelane_b32 v253, s22, 8
	v_writelane_b32 v253, s23, 9
	v_writelane_b32 v253, s24, 10
	v_writelane_b32 v253, s25, 11
	v_writelane_b32 v253, s26, 12
	v_writelane_b32 v253, s27, 13
	v_writelane_b32 v253, s28, 14
	v_writelane_b32 v253, s29, 15
	v_writelane_b32 v253, s30, 16
	v_writelane_b32 v253, s31, 17
	v_writelane_b32 v253, s4, 18
	s_addc_u32 s4, s95, 0
	v_writelane_b32 v253, s4, 19
	s_add_u32 s4, s94, 0x1a00000
	v_writelane_b32 v253, s4, 20
	s_addc_u32 s4, s95, 0
	v_writelane_b32 v253, s4, 21
	s_add_u32 s4, s94, 0x3a00000
	v_writelane_b32 v253, s4, 22
	s_addc_u32 s4, s95, 0
	v_writelane_b32 v253, s4, 23
	s_lshl_b32 s4, s52, 3
	s_add_i32 s12, s14, s4
	s_lshl_b32 s38, s60, 3
	s_mov_b32 s54, s4
	s_cmpk_gt_i32 s12, 0x167f
	s_barrier
	s_cbranch_scc1 .LBB0_50
	v_lshlrev_b32_e32 v1, 3, v2
	s_lshl_b32 s4, s14, 14
	v_lshrrev_b32_e32 v5, 3, v2
	v_and_b32_e32 v14, 56, v1
	s_add_i32 s4, s4, 0
	v_lshrrev_b32_e32 v6, 5, v2
	v_and_b32_e32 v8, 31, v4
	v_mul_u32_u24_e32 v1, 0x84, v14
	v_lshlrev_b32_e32 v3, 2, v5
	v_mov_b32_e32 v9, 0
	v_lshl_add_u32 v10, v8, 2, s4
	s_movk_i32 s13, 0x84
	v_add3_u32 v7, s4, v1, v3
	v_or_b32_e32 v11, 8, v5
	v_or_b32_e32 v19, 16, v5
	v_or_b32_e32 v20, 24, v5
	v_mov_b32_e32 v1, v6
	s_movk_i32 s14, 0x7fff
	s_mov_b32 s15, 0xffff0000
	s_movk_i32 s16, 0x2400
	v_lshlrev_b32_e32 v12, 2, v8
	v_lshlrev_b32_e32 v14, 1, v14
	s_mov_b32 s56, s38
	s_branch .LBB0_30
.LBB0_29:
	s_add_i32 s12, s12, s38
	s_cmpk_gt_i32 s12, 0x167f
	s_cbranch_scc1 .LBB0_50

; #define LAS __attribute__((address_space(3)))
; template <bool PERMIN> __device__ __forceinline__ void transpose_item(const float* W, int K, int N, bf16* WT, LAS float* scr, int item, int lane) {
;     const int nblk = N / 32, kb = item / nblk, nb = item % nblk, k0 = 64 * kb, n0 = 32 * nb;
; #pragma unroll 8
;     for (int i = 0; i < 32; ++i) { const int kk = 2 * i + (lane >> 5); scr[kk * 33 + (lane & 31)] = W[(size_t)(k0 + kk) * N + n0 + (lane & 31)]; }
;     asm volatile("s_waitcnt lgkmcnt(0)" ::: "memory");
;     int r0 = n0;
;     if (PERMIN) { const int cl = n0 & 255; r0 = (n0 & ~255) + 128 * ((cl >> 5) & 1) + 32 * (cl >> 6); }
; __global__ void __launch_bounds__(NTHR, 2) trunk_fwd(Args a) {
;     ...
;         for (int it = gw; it < DEPTH * I_L; it += ngw) { const int l = it / I_L; int r = it % I_L;
;             if (r < I_IN) { transpose_item<true>(a.w_in + (size_t)l * DM * DIN, DM, DIN, WT_IN + (size_t)l * DIN * DM, scr, r, lane); continue; } r -= I_IN;
;             if (r < I_OUT) { transpose_item<true>(a.w_out + (size_t)l * DM * DM, DM, DM, WT_OUT + (size_t)l * DM * DM, scr, r, lane); continue; } r -= I_OUT;
;             if (r < I_1) { transpose_item<true>(a.w_ff1 + (size_t)l * DM * DFF, DM, DFF, WT_1 + (size_t)l * DFF * DM, scr, r, lane); continue; } r -= I_1;
;             transpose_item<true>(a.w_ff2 + (size_t)l * DFF * DM, DFF, DM, WT_2 + (size_t)l * DM * DFF, scr, r, lane); }
.LBB0_1346:
	s_waitcnt vmcnt(0)
	v_readlane_b32 s52, v255, 58
	v_readlane_b32 s53, v255, 59
	s_mov_b64 s[50:51], 0x1800
	s_barrier
	v_readlane_b32 s37, v253, 41
	v_readlane_b32 s30, v253, 57
	v_readlane_b32 s31, v253, 58
	v_readfirstlane_b32 s38, v212
	s_nop 3
	s_cmp_lt_u32 s79, 0x80
	s_cbranch_scc1 .Ldtx_skip
	s_cmp_gt_u32 s37, 2
	s_cbranch_scc1 .Ldtx_skip
	s_load_dwordx2 s[28:29], s[30:31], 0x30
	s_load_dwordx2 s[18:19], s[30:31], 0x88
	s_load_dwordx4 s[24:27], s[30:31], 0xa0
	s_mov_b32 s20, s4
	s_mov_b32 s21, s5
	s_mov_b32 s22, s6
	s_mov_b32 s23, s12
	s_mov_b32 s34, s14
	s_mov_b32 s35, s15
	s_mov_b32 s36, s46
	s_add_u32 s37, s37, 1
	s_mul_i32 s12, s37, 0x1680
	s_add_u32 s39, s12, 0x1680
	s_lshr_b32 s38, s38, 6
	s_sub_u32 s4, s79, 0x80
	s_lshl_b32 s4, s4, 3
	s_add_u32 s12, s12, s4
	s_add_u32 s12, s12, s38
	s_movk_i32 s38, 0x400
	s_waitcnt lgkmcnt(0)
.Ldtx_entry:
	v_mbcnt_lo_u32_b32 v5, -1, 0
	v_mbcnt_hi_u32_b32 v5, -1, v5
	v_readfirstlane_b32 s4, v212
	v_lshrrev_b32_e32 v6, 3, v5
	v_and_b32_e32 v7, 7, v5
	v_lshlrev_b32_e32 v7, 4, v7
	s_nop 1
	s_lshr_b32 s4, s4, 6
	s_lshl_b32 s4, s4, 14
	v_mul_u32_u24_e32 v8, 0x84, v6
	v_add3_u32 v8, v8, v7, s4
	v_mul_u32_u24_e32 v9, 66, v7
	v_lshl_add_u32 v9, v6, 2, v9
	v_add_u32_e32 v9, s4, v9
	s_cmp_lt_u32 s12, s39
	s_cbranch_scc0 .Ldtx_done
	s_mov_b32 s4, 0
	s_mov_b32 s5, s12
	s_cmp_ge_u32 s5, 0x1680
	s_cselect_b32 s6, 0x1680, 0
	s_cselect_b32 s7, 1, 0
	s_sub_u32 s5, s5, s6
	s_add_u32 s4, s4, s7
	s_cmp_ge_u32 s5, 0x1680
	s_cselect_b32 s6, 0x1680, 0
	s_cselect_b32 s7, 1, 0
	s_sub_u32 s5, s5, s6
	s_add_u32 s4, s4, s7
	s_cmp_ge_u32 s5, 0x1680
	s_cselect_b32 s6, 0x1680, 0
	s_cselect_b32 s7, 1, 0
	s_sub_u32 s5, s5, s6
	s_add_u32 s4, s4, s7
	s_cmp_lt_u32 s5, 0x480
	s_cbranch_scc0 .Ldtx_p_c1
	s_mul_i32 s6, s4, 0x900000
	s_add_u32 s14, s28, s6
	s_addc_u32 s15, s29, 0
	s_mul_i32 s6, s4, 0x480000
	s_add_u32 s16, s94, s6
	s_addc_u32 s17, s95, 0
	s_mul_hi_u32 s8, s5, 0x38e38e4
	s_mul_i32 s6, s8, 72
	s_sub_u32 s9, s5, s6
	s_movk_i32 s10, 0x900
	s_movk_i32 s11, 0x400
	s_branch .Ldtx_p_join

; __global__ void __launch_bounds__(NTHR, 2) trunk_fwd(Args a) {
;     ...
;         for (int it = gw; it < DEPTH * I_L; it += ngw) { const int l = it / I_L; int r = it % I_L;
;             if (r < I_IN) { transpose_item<true>(a.w_in + (size_t)l * DM * DIN, DM, DIN, WT_IN + (size_t)l * DIN * DM, scr, r, lane); continue; } r -= I_IN;
;             if (r < I_OUT) { transpose_item<true>(a.w_out + (size_t)l * DM * DM, DM, DM, WT_OUT + (size_t)l * DM * DM, scr, r, lane); continue; } r -= I_OUT;
;             if (r < I_1) { transpose_item<true>(a.w_ff1 + (size_t)l * DM * DFF, DM, DFF, WT_1 + (size_t)l * DFF * DM, scr, r, lane); continue; } r -= I_1;
;             transpose_item<true>(a.w_ff2 + (size_t)l * DFF * DM, DFF, DM, WT_2 + (size_t)l * DM * DFF, scr, r, lane); }
.Ldtx_loop:
	s_add_u32 s13, s12, s38
	s_cmp_lt_u32 s13, s39
	s_cbranch_scc0 .Ldtx_last_0
	s_mov_b32 s4, 0
	s_mov_b32 s5, s13
	s_cmp_ge_u32 s5, 0x1680
	s_cselect_b32 s6, 0x1680, 0
	s_cselect_b32 s7, 1, 0
	s_sub_u32 s5, s5, s6
	s_add_u32 s4, s4, s7
	s_cmp_ge_u32 s5, 0x1680
	s_cselect_b32 s6, 0x1680, 0
	s_cselect_b32 s7, 1, 0
	s_sub_u32 s5, s5, s6
	s_add_u32 s4, s4, s7
	s_cmp_ge_u32 s5, 0x1680
	s_cselect_b32 s6, 0x1680, 0
	s_cselect_b32 s7, 1, 0
	s_sub_u32 s5, s5, s6
	s_add_u32 s4, s4, s7
	s_cmp_lt_u32 s5, 0x480
	s_cbranch_scc0 .Ldtx_l0_c1
	s_mul_i32 s6, s4, 0x900000
	s_add_u32 s14, s28, s6
	s_addc_u32 s15, s29, 0
	s_mul_i32 s6, s4, 0x480000
	s_add_u32 s16, s94, s6
	s_addc_u32 s17, s95, 0
	s_mul_hi_u32 s8, s5, 0x38e38e4
	s_mul_i32 s6, s8, 72
	s_sub_u32 s9, s5, s6
	s_movk_i32 s10, 0x900
	s_movk_i32 s11, 0x400
	s_branch .Ldtx_l0_join

; #define LAS __attribute__((address_space(3)))
; __device__ __forceinline__ unsigned pk2(float lo, float hi) { return f2bf(lo) | (f2bf(hi) << 16); }
; template <bool PERMIN> __device__ __forceinline__ void transpose_item(const float* W, int K, int N, bf16* WT, LAS float* scr, int item, int lane) {
;     const int nblk = N / 32, kb = item / nblk, nb = item % nblk, k0 = 64 * kb, n0 = 32 * nb;
; #pragma unroll 8
;     for (int i = 0; i < 32; ++i) { const int kk = 2 * i + (lane >> 5); scr[kk * 33 + (lane & 31)] = W[(size_t)(k0 + kk) * N + n0 + (lane & 31)]; }
;     asm volatile("s_waitcnt lgkmcnt(0)" ::: "memory");
;     int r0 = n0;
;     if (PERMIN) { const int cl = n0 & 255; r0 = (n0 & ~255) + 128 * ((cl >> 5) & 1) + 32 * (cl >> 6); }
;     const int c = lane & 7;
; #pragma unroll
;     for (int j = 0; j < 4; ++j) { const int n = (lane >> 3) + 8 * j; const LAS float* s = scr + (8 * c) * 33 + n;
;         v4u o; o.x = pk2(s[0 * 33], s[1 * 33]); o.y = pk2(s[2 * 33], s[3 * 33]); o.z = pk2(s[4 * 33], s[5 * 33]); o.w = pk2(s[6 * 33], s[7 * 33]);
;         *(v4u*)(WT + (size_t)(r0 + n) * K + k0 + 8 * c) = o; }
;     asm volatile("s_waitcnt lgkmcnt(0)" ::: "memory");
; }
.Ldtx_proc_0:
	ds_write_b32 v8, v16 offset:0
	ds_write_b32 v8, v17 offset:4
	ds_write_b32 v8, v18 offset:8
	ds_write_b32 v8, v19 offset:12
	ds_write_b32 v8, v20 offset:1056
	ds_write_b32 v8, v21 offset:1060
	ds_write_b32 v8, v22 offset:1064
	ds_write_b32 v8, v23 offset:1068
	ds_write_b32 v8, v24 offset:2112
	ds_write_b32 v8, v25 offset:2116
	ds_write_b32 v8, v26 offset:2120
	ds_write_b32 v8, v27 offset:2124
	ds_write_b32 v8, v28 offset:3168
	ds_write_b32 v8, v29 offset:3172
	ds_write_b32 v8, v30 offset:3176
	ds_write_b32 v8, v31 offset:3180
	ds_write_b32 v8, v32 offset:4224
	ds_write_b32 v8, v33 offset:4228
	ds_write_b32 v8, v34 offset:4232
	ds_write_b32 v8, v35 offset:4236
	ds_write_b32 v8, v36 offset:5280
	ds_write_b32 v8, v37 offset:5284
	ds_write_b32 v8, v38 offset:5288
	ds_write_b32 v8, v39 offset:5292
	ds_write_b32 v8, v40 offset:6336
	ds_write_b32 v8, v41 offset:6340
	ds_write_b32 v8, v42 offset:6344
	ds_write_b32 v8, v43 offset:6348
	ds_write_b32 v8, v44 offset:7392
	ds_write_b32 v8, v45 offset:7396
	ds_write_b32 v8, v46 offset:7400
	ds_write_b32 v8, v47 offset:7404
	s_waitcnt lgkmcnt(0)
	ds_read_b32 v130, v9 offset:0
	ds_read_b32 v131, v9 offset:132
	ds_read_b32 v132, v9 offset:264
	ds_read_b32 v133, v9 offset:396
	ds_read_b32 v134, v9 offset:528
	ds_read_b32 v135, v9 offset:660
	ds_read_b32 v136, v9 offset:792
	ds_read_b32 v137, v9 offset:924
	ds_read_b32 v138, v9 offset:32
	ds_read_b32 v139, v9 offset:164
	ds_read_b32 v140, v9 offset:296
	ds_read_b32 v141, v9 offset:428
	ds_read_b32 v142, v9 offset:560
	ds_read_b32 v143, v9 offset:692
	ds_read_b32 v144, v9 offset:824
	ds_read_b32 v145, v9 offset:956
	v_mul_lo_u32 v11, s42, v6
	v_add_u32_e32 v11, v11, v7
	s_lshl_b32 s6, s42, 3
	s_waitcnt lgkmcnt(8)
	v_cvt_pk_bf16_f32 v162, v130, v131
	v_cvt_pk_bf16_f32 v163, v132, v133
	v_cvt_pk_bf16_f32 v164, v134, v135
	v_cvt_pk_bf16_f32 v165, v136, v137
	ds_read_b32 v146, v9 offset:64
	ds_read_b32 v147, v9 offset:196
	ds_read_b32 v148, v9 offset:328
	ds_read_b32 v149, v9 offset:460
	ds_read_b32 v150, v9 offset:592
	ds_read_b32 v151, v9 offset:724
	ds_read_b32 v152, v9 offset:856
	ds_read_b32 v153, v9 offset:988
	global_store_dwordx4 v11, v[162:165], s[40:41]
	v_add_u32_e32 v11, s6, v11
	s_waitcnt lgkmcnt(8)
	v_cvt_pk_bf16_f32 v166, v138, v139
	v_cvt_pk_bf16_f32 v167, v140, v141
	v_cvt_pk_bf16_f32 v168, v142, v143
	v_cvt_pk_bf16_f32 v169, v144, v145
	ds_read_b32 v154, v9 offset:96
	ds_read_b32 v155, v9 offset:228
	ds_read_b32 v156, v9 offset:360
	ds_read_b32 v157, v9 offset:492
	ds_read_b32 v158, v9 offset:624
	ds_read_b32 v159, v9 offset:756
	ds_read_b32 v160, v9 offset:888
	ds_read_b32 v161, v9 offset:1020
	global_store_dwordx4 v11, v[166:169], s[40:41]
	v_add_u32_e32 v11, s6, v11
	s_waitcnt lgkmcnt(8)
	v_cvt_pk_bf16_f32 v170, v146, v147
	v_cvt_pk_bf16_f32 v171, v148, v149
	v_cvt_pk_bf16_f32 v172, v150, v151
	v_cvt_pk_bf16_f32 v173, v152, v153
	global_store_dwordx4 v11, v[170:173], s[40:41]
	v_add_u32_e32 v11, s6, v11
	s_waitcnt lgkmcnt(0)
	v_cvt_pk_bf16_f32 v174, v154, v155
	v_cvt_pk_bf16_f32 v175, v156, v157
	v_cvt_pk_bf16_f32 v176, v158, v159
	v_cvt_pk_bf16_f32 v177, v160, v161
	global_store_dwordx4 v11, v[174:177], s[40:41]
	s_mov_b32 s12, s13
	s_cmp_lt_u32 s12, s39
	s_cbranch_scc0 .Ldtx_done
	s_add_u32 s13, s12, s38
	s_cmp_lt_u32 s13, s39
	s_cbranch_scc0 .Ldtx_last_1
	s_mov_b32 s4, 0
	s_mov_b32 s5, s13
	s_cmp_ge_u32 s5, 0x1680
	s_cselect_b32 s6, 0x1680, 0
	s_cselect_b32 s7, 1, 0
	s_sub_u32 s5, s5, s6
	s_add_u32 s4, s4, s7
	s_cmp_ge_u32 s5, 0x1680
	s_cselect_b32 s6, 0x1680, 0
	s_cselect_b32 s7, 1, 0
	s_sub_u32 s5, s5, s6
	s_add_u32 s4, s4, s7
	s_cmp_ge_u32 s5, 0x1680
	s_cselect_b32 s6, 0x1680, 0
	s_cselect_b32 s7, 1, 0
	s_sub_u32 s5, s5, s6
	s_add_u32 s4, s4, s7
	s_cmp_lt_u32 s5, 0x480
	s_cbranch_scc0 .Ldtx_l1_c1
	s_mul_i32 s6, s4, 0x900000
	s_add_u32 s14, s28, s6
	s_addc_u32 s15, s29, 0
	s_mul_i32 s6, s4, 0x480000
	s_add_u32 s16, s94, s6
	s_addc_u32 s17, s95, 0
	s_mul_hi_u32 s8, s5, 0x38e38e4
	s_mul_i32 s6, s8, 72
	s_sub_u32 s9, s5, s6
	s_movk_i32 s10, 0x900
	s_movk_i32 s11, 0x400
	s_branch .Ldtx_l1_join

; #define LAS __attribute__((address_space(3)))
; __device__ __forceinline__ unsigned pk2(float lo, float hi) { return f2bf(lo) | (f2bf(hi) << 16); }
; template <bool PERMIN> __device__ __forceinline__ void transpose_item(const float* W, int K, int N, bf16* WT, LAS float* scr, int item, int lane) {
;     const int nblk = N / 32, kb = item / nblk, nb = item % nblk, k0 = 64 * kb, n0 = 32 * nb;
; #pragma unroll 8
;     for (int i = 0; i < 32; ++i) { const int kk = 2 * i + (lane >> 5); scr[kk * 33 + (lane & 31)] = W[(size_t)(k0 + kk) * N + n0 + (lane & 31)]; }
;     asm volatile("s_waitcnt lgkmcnt(0)" ::: "memory");
;     int r0 = n0;
;     if (PERMIN) { const int cl = n0 & 255; r0 = (n0 & ~255) + 128 * ((cl >> 5) & 1) + 32 * (cl >> 6); }
;     const int c = lane & 7;
; #pragma unroll
;     for (int j = 0; j < 4; ++j) { const int n = (lane >> 3) + 8 * j; const LAS float* s = scr + (8 * c) * 33 + n;
;         v4u o; o.x = pk2(s[0 * 33], s[1 * 33]); o.y = pk2(s[2 * 33], s[3 * 33]); o.z = pk2(s[4 * 33], s[5 * 33]); o.w = pk2(s[6 * 33], s[7 * 33]);
;         *(v4u*)(WT + (size_t)(r0 + n) * K + k0 + 8 * c) = o; }
;     asm volatile("s_waitcnt lgkmcnt(0)" ::: "memory");
; }
.Ldtx_proc_1:
	ds_write_b32 v8, v48 offset:0
	ds_write_b32 v8, v49 offset:4
	ds_write_b32 v8, v50 offset:8
	ds_write_b32 v8, v51 offset:12
	ds_write_b32 v8, v52 offset:1056
	ds_write_b32 v8, v53 offset:1060
	ds_write_b32 v8, v54 offset:1064
	ds_write_b32 v8, v55 offset:1068
	ds_write_b32 v8, v56 offset:2112
	ds_write_b32 v8, v57 offset:2116
	ds_write_b32 v8, v58 offset:2120
	ds_write_b32 v8, v59 offset:2124
	ds_write_b32 v8, v60 offset:3168
	ds_write_b32 v8, v61 offset:3172
	ds_write_b32 v8, v62 offset:3176
	ds_write_b32 v8, v63 offset:3180
	ds_write_b32 v8, v64 offset:4224
	ds_write_b32 v8, v65 offset:4228
	ds_write_b32 v8, v66 offset:4232
	ds_write_b32 v8, v67 offset:4236
	ds_write_b32 v8, v68 offset:5280
	ds_write_b32 v8, v69 offset:5284
	ds_write_b32 v8, v70 offset:5288
	ds_write_b32 v8, v71 offset:5292
	ds_write_b32 v8, v72 offset:6336
	ds_write_b32 v8, v73 offset:6340
	ds_write_b32 v8, v74 offset:6344
	ds_write_b32 v8, v75 offset:6348
	ds_write_b32 v8, v76 offset:7392
	ds_write_b32 v8, v77 offset:7396
	ds_write_b32 v8, v78 offset:7400
	ds_write_b32 v8, v79 offset:7404
	s_waitcnt lgkmcnt(0)
	ds_read_b32 v130, v9 offset:0
	ds_read_b32 v131, v9 offset:132
	ds_read_b32 v132, v9 offset:264
	ds_read_b32 v133, v9 offset:396
	ds_read_b32 v134, v9 offset:528
	ds_read_b32 v135, v9 offset:660
	ds_read_b32 v136, v9 offset:792
	ds_read_b32 v137, v9 offset:924
	ds_read_b32 v138, v9 offset:32
	ds_read_b32 v139, v9 offset:164
	ds_read_b32 v140, v9 offset:296
	ds_read_b32 v141, v9 offset:428
	ds_read_b32 v142, v9 offset:560
	ds_read_b32 v143, v9 offset:692
	ds_read_b32 v144, v9 offset:824
	ds_read_b32 v145, v9 offset:956
	v_mul_lo_u32 v11, s46, v6
	v_add_u32_e32 v11, v11, v7
	s_lshl_b32 s6, s46, 3
	s_waitcnt lgkmcnt(8)
	v_cvt_pk_bf16_f32 v162, v130, v131
	v_cvt_pk_bf16_f32 v163, v132, v133
	v_cvt_pk_bf16_f32 v164, v134, v135
	v_cvt_pk_bf16_f32 v165, v136, v137
	ds_read_b32 v146, v9 offset:64
	ds_read_b32 v147, v9 offset:196
	ds_read_b32 v148, v9 offset:328
	ds_read_b32 v149, v9 offset:460
	ds_read_b32 v150, v9 offset:592
	ds_read_b32 v151, v9 offset:724
	ds_read_b32 v152, v9 offset:856
	ds_read_b32 v153, v9 offset:988
	global_store_dwordx4 v11, v[162:165], s[44:45]
	v_add_u32_e32 v11, s6, v11
	s_waitcnt lgkmcnt(8)
	v_cvt_pk_bf16_f32 v166, v138, v139
	v_cvt_pk_bf16_f32 v167, v140, v141
	v_cvt_pk_bf16_f32 v168, v142, v143
	v_cvt_pk_bf16_f32 v169, v144, v145
	ds_read_b32 v154, v9 offset:96
	ds_read_b32 v155, v9 offset:228
	ds_read_b32 v156, v9 offset:360
	ds_read_b32 v157, v9 offset:492
	ds_read_b32 v158, v9 offset:624
	ds_read_b32 v159, v9 offset:756
	ds_read_b32 v160, v9 offset:888
	ds_read_b32 v161, v9 offset:1020
	global_store_dwordx4 v11, v[166:169], s[44:45]
	v_add_u32_e32 v11, s6, v11
	s_waitcnt lgkmcnt(8)
	v_cvt_pk_bf16_f32 v170, v146, v147
	v_cvt_pk_bf16_f32 v171, v148, v149
	v_cvt_pk_bf16_f32 v172, v150, v151
	v_cvt_pk_bf16_f32 v173, v152, v153
	global_store_dwordx4 v11, v[170:173], s[44:45]
	v_add_u32_e32 v11, s6, v11
	s_waitcnt lgkmcnt(0)
	v_cvt_pk_bf16_f32 v174, v154, v155
	v_cvt_pk_bf16_f32 v175, v156, v157
	v_cvt_pk_bf16_f32 v176, v158, v159
	v_cvt_pk_bf16_f32 v177, v160, v161
	global_store_dwordx4 v11, v[174:177], s[44:45]
	s_mov_b32 s12, s13
	s_cmp_lt_u32 s12, s39
	s_cbranch_scc0 .Ldtx_done
	s_branch .Ldtx_loop
.Ldtx_done:
	s_waitcnt vmcnt(0) lgkmcnt(0)
	s_mov_b32 s4, s20
	s_mov_b32 s5, s21
	s_mov_b32 s6, s22
	s_mov_b32 s12, s23
	s_mov_b32 s14, s34
	s_mov_b32 s15, s35
	s_mov_b32 s46, s36
.Ldtx_skip:
.LBB0_1347:
	s_getreg_b32 s16, hwreg(HW_REG_XCC_ID, 0, 4)
	s_waitcnt vmcnt(0)
	v_readlane_b32 s2, v252, 0
	v_readlane_b32 s3, v252, 1
	s_waitcnt vmcnt(0)
	s_barrier
	s_and_saveexec_b64 s[0:1], s[2:3]
	s_xor_b64 s[0:1], exec, s[0:1]
	s_cbranch_execz .LBB0_1400
	v_readlane_b32 s2, v255, 46
	s_waitcnt vmcnt(0) expcnt(0) lgkmcnt(0)
	s_and_b32 s22, s16, 15
	v_mov_b32_e32 v0, s2
	ds_read_b32 v3, v0
	v_readlane_b32 s2, v255, 47
	s_waitcnt lgkmcnt(0)
	v_cmp_ne_u32_e32 vcc, 0, v3
	v_mov_b32_e32 v0, s2
	ds_read_b32 v2, v0
	s_cbranch_vccnz .LBB0_1363
	s_mov_b32 s23, 1
	s_branch .LBB0_1351
